# v6 without setprio + waves 4-7 start each NSA tile s_sleep 8 later (SIMD partner waves out of phase: MFMA vs VALU)
# baseline (speedup 1.0000x reference)
; __device__ __forceinline__ int tid_() { int t = threadIdx.x; asm volatile("" : "+v"(t)); return t; }
; #define LAS __attribute__((address_space(3)))
;     unsigned* ctr = (unsigned*)(a->ws + WS_CTL) + 64 * (l + 2 * rep);
;     for (;;) {
;         __syncthreads();
;         if (tid_() == 0) *(LAS int*)(lds + NSA_ITEM) = (int)atomicAdd(ctr, 1u);
;         __syncthreads();
;         const int it = *(LAS int*)(lds + NSA_ITEM);
;         if (it >= 1024) break;
;         nsa_item(a, lds, it);
;     }
; }
.LBB0_599:
	s_load_dwordx2 s[0:1], s[12:13], 0x120
	s_waitcnt lgkmcnt(0)
	s_add_u32 s2, s0, s10
	s_addc_u32 s3, s1, s11
	v_writelane_b32 v254, s2, 37
	s_nop 1
	v_writelane_b32 v254, s3, 38
	s_add_u32 s2, s0, 0x8000000
	s_addc_u32 s3, s1, 0
	v_writelane_b32 v254, s2, 39
	s_nop 1
	v_writelane_b32 v254, s3, 40
	s_add_u32 s2, s0, 0x180000
	v_writelane_b32 v254, s2, 41
	s_addc_u32 s2, s1, 0
	v_writelane_b32 v254, s2, 42
	s_add_u32 s2, s0, 0x200000
	v_writelane_b32 v254, s2, 43
	v_writelane_b32 v254, s0, 44
	s_nop 1
	v_writelane_b32 v254, s1, 45
	s_addc_u32 s0, s1, 0
	v_writelane_b32 v254, s0, 46
	v_readfirstlane_b32 s101, v232
	s_nop 3
	s_lshr_b32 s101, s101, 8
	s_branch .LBB0_603

; #define LAS __attribute__((address_space(3)))
; DI f32x16 mma32(bf16x8 a, bf16x8 b, f32x16 c) { return __builtin_amdgcn_mfma_f32_32x32x16_bf16(a, b, c, 0, 0, 0); }
; DI void nsa_item(KA a, LAS unsigned char* lds, const int it) {
;     ...
;     for (int i = 0; i < n; ++i) {
;         const int desc = LIST[i]; const int ty = desc >> 8, j = desc & 255;
;         const LAS bf16* Kc = (i & 1) ? Kt1 : Kt; const LAS bf16* Vc = (i & 1) ? VT1 : VT;
;         if (ty != curtype) { const float lt = l_run + __shfl_xor(l_run, 32); const float sc = g1 / lt; of[0] += ot[0] * sc; of[1] += ot[1] * sc; ot[0] = ZERO16; ot[1] = ZERO16; m_ref = 0.f; l_run = 0.f; curtype = ty; }
;         const bool rowoff = (ty == 0) && (((mysel >> j) & 1u) == 0u);
;         const int mode = (j == qb) ? 1 : ((ty == 1 && j == qb - 8) ? 2 : 0);
;         const float init = rowoff ? -INFINITY : -m_ref;
;         f32x16 st[2];
; #pragma unroll
;         for (int i2 = 0; i2 < 16; ++i2) { st[0][i2] = init; st[1][i2] = init; }
; #pragma unroll
;         for (int kt = 0; kt < 2; ++kt)
; #pragma unroll
;             for (int s = 0; s < 4; ++s) { const bf16x8 af = *(const LAS bf16x8*)(Kc + (32 * kt + r) * PA + 16 * s + 8 * hf); st[kt] = mma32(af, bq[s], st[kt]); }
.LBB0_796:
	s_cmp_eq_u32 s101, 0
	s_cbranch_scc1 .Lnsa_nostag
	s_sleep 8
